# LN2 phases: YE rows of the next row's first expert pair prefetched during the current row's LayerNorm math (both layers)
# speedup vs baseline: 1.0059x; 1.0036x over previous
.LBB0_1837:
	s_or_b64 exec, exec, s[18:19]
	s_add_u32 s27, s16, 0x6fc18000
	s_addc_u32 s28, s17, 0
	s_lshl_b64 s[18:19], s[22:23], 3
	s_add_u32 s18, s27, s18
	s_addc_u32 s19, s28, s19
	global_load_dwordx2 v[44:45], v33, s[18:19]
	v_and_b32_e32 v80, 64, v4
	v_add_u32_e32 v0, 64, v80
	v_xor_b32_e32 v1, 1, v4
	v_cmp_lt_i32_e32 vcc, v1, v0
	v_lshl_add_u64 v[2:3], s[16:17], 0, v[32:33]
	s_mov_b64 s[18:19], 0x333d8000
	v_cndmask_b32_e32 v1, v4, v1, vcc
	v_lshlrev_b32_e32 v81, 2, v1
	v_xor_b32_e32 v1, 2, v4
	v_cmp_lt_i32_e32 vcc, v1, v0
	v_lshl_add_u32 v87, v32, 2, 0
	v_mov_b32_e32 v88, 0x3727c5ac
	v_cndmask_b32_e32 v1, v4, v1, vcc
	v_lshlrev_b32_e32 v82, 2, v1
	v_xor_b32_e32 v1, 4, v4
	v_cmp_lt_i32_e32 vcc, v1, v0
	v_mov_b32_e32 v89, v33
	s_nop 0
	v_cndmask_b32_e32 v1, v4, v1, vcc
	v_lshlrev_b32_e32 v83, 2, v1
	v_xor_b32_e32 v1, 8, v4
	v_cmp_lt_i32_e32 vcc, v1, v0
	s_nop 1
	v_cndmask_b32_e32 v1, v4, v1, vcc
	v_lshlrev_b32_e32 v84, 2, v1
	v_xor_b32_e32 v1, 16, v4
	v_cmp_lt_i32_e32 vcc, v1, v0
	s_nop 1
	v_cndmask_b32_e32 v1, v4, v1, vcc
	v_lshlrev_b32_e32 v85, 2, v1
	v_xor_b32_e32 v1, 32, v4
	v_cmp_lt_i32_e32 vcc, v1, v0
	s_nop 1
	v_cndmask_b32_e32 v0, v4, v1, vcc
	v_lshlrev_b32_e32 v86, 2, v0
	v_lshlrev_b32_e32 v0, 1, v32
	v_mov_b32_e32 v1, v33
	v_lshl_add_u64 v[34:35], s[14:15], 0, v[0:1]
	s_mov_b64 s[14:15], 0x68358000
	v_lshl_add_u64 v[36:37], v[2:3], 0, s[14:15]
	s_mov_b32 s15, 0
	v_lshl_add_u64 v[0:1], s[16:17], 0, v[0:1]
	s_mov_b64 s[16:17], 0x561d8000
	v_lshl_add_u64 v[38:39], v[0:1], 0, s[16:17]
	s_mov_b32 s17, 1.0
	s_mov_b32 s16, s15
	v_lshl_add_u64 v[40:41], v[0:1], 0, s[18:19]
	v_mov_b64_e32 v[42:43], s[16:17]
	s_mov_b32 s16, 0x3fb504f3
	s_mov_b32 s17, 0x800000
	s_mov_b32 s98, 0
	s_branch .LBB0_1840

.LBB0_1839:
	s_add_i32 s14, s22, 0xfffff000
	s_lshr_b32 s14, s14, 10
	s_add_i32 s14, s14, 1
	s_cmpk_gt_i32 s22, 0xfff
	s_cselect_b32 s14, s14, 0
	s_sub_i32 s14, s14, s3
	v_lshlrev_b32_e32 v32, 16, v28
	v_and_b32_e32 v90, 0xffff0000, v28
	s_mulk_i32 s14, 0x6000
	s_waitcnt vmcnt(0)
	s_mov_b32 s98, 0
	s_and_b64 vcc, exec, s[20:21]
	s_cbranch_vccnz .Ln0_pfdone
	v_cmp_lt_i32_e32 vcc, -1, v79
	s_and_b32 s100, vcc_lo, 0xffff
	s_mov_b32 s101, 0
	s_cmp_eq_u64 s[100:101], 0
	s_cbranch_scc1 .Ln0_pfdone
	s_ff1_i32_b64 s19, s[100:101]
	s_add_u32 s30, s100, -1
	s_addc_u32 s31, s101, -1
	s_and_b64 s[100:101], s[30:31], s[100:101]
	s_cmp_eq_u64 s[100:101], 0
	s_cselect_b64 s[30:31], -1, 0
	s_ff1_i32_b64 s24, s[100:101]
	s_and_b64 vcc, s[30:31], exec
	s_cselect_b32 s24, s19, s24
	v_or_b32_e32 v218, s19, v80
	v_or_b32_e32 v219, s24, v80
	v_lshlrev_b32_e32 v218, 2, v218
	v_lshlrev_b32_e32 v219, 2, v219
	ds_bpermute_b32 v220, v218, v79
	ds_bpermute_b32 v221, v219, v79
	ds_bpermute_b32 v216, v218, v89
	ds_bpermute_b32 v217, v219, v89
	s_mulk_i32 s19, 0x600
	s_mulk_i32 s24, 0x600
	s_add_u32 s30, s100, -1
	s_addc_u32 s31, s101, -1
	s_and_b64 s[100:101], s[30:31], s[100:101]
	s_waitcnt lgkmcnt(0)
	v_add_u32_e32 v220, s19, v220
	v_add_u32_e32 v222, s24, v221
	v_ashrrev_i32_e32 v221, 31, v220
	v_ashrrev_i32_e32 v223, 31, v222
	v_lshlrev_b64 v[220:221], 11, v[220:221]
	v_lshlrev_b64 v[222:223], 11, v[222:223]
	v_lshl_add_u64 v[220:221], v[36:37], 0, v[220:221]
	v_lshl_add_u64 v[222:223], v[36:37], 0, v[222:223]
	global_load_dwordx2 v[200:201], v[220:221], off
	global_load_dwordx2 v[202:203], v[222:223], off
	global_load_dwordx2 v[204:205], v[220:221], off offset:512
	global_load_dwordx2 v[206:207], v[222:223], off offset:512
	global_load_dwordx2 v[208:209], v[220:221], off offset:1024
	global_load_dwordx2 v[210:211], v[222:223], off offset:1024
	global_load_dwordx2 v[212:213], v[220:221], off offset:1536
	global_load_dwordx2 v[214:215], v[222:223], off offset:1536
	v_mul_f32_e32 v216, 0x3e000000, v216
	v_mul_f32_e32 v217, 0x3e000000, v217
	s_cmp_eq_u32 s24, s19
	s_cbranch_scc0 .Ln0_two
	v_mov_b32_e32 v217, 0
.Ln0_two:
	s_mov_b32 s98, 1
.Ln0_pfdone:
	v_sub_f32_e32 v91, v90, v44
	v_sub_f32_e32 v90, v32, v44
	ds_read_b128 v[92:95], v87
	ds_read_b128 v[96:99], v87 offset:8192
	v_pk_mul_f32 v[112:113], v[44:45], v[90:91] op_sel:[1,0]
	v_add_u32_e32 v90, s14, v87
	v_lshlrev_b32_e32 v28, 16, v29
	v_and_b32_e32 v29, 0xffff0000, v29
	ds_read_b128 v[100:103], v87 offset:16
	ds_read_b128 v[104:107], v87 offset:8208
	ds_read_b128 v[108:111], v90 offset:32768
	v_sub_f32_e32 v29, v29, v44
	v_sub_f32_e32 v28, v28, v44
	v_pk_mul_f32 v[28:29], v[44:45], v[28:29] op_sel:[1,0]
	s_waitcnt lgkmcnt(3)
	v_pk_fma_f32 v[92:93], v[112:113], v[92:93], v[96:97]
	v_pk_fma_f32 v[28:29], v[28:29], v[94:95], v[98:99]
	v_pk_mul_f32 v[96:97], v[92:93], s[16:17] op_sel_hi:[1,0]
	v_pk_mul_f32 v[28:29], v[28:29], s[16:17] op_sel_hi:[1,0]
	ds_read_b128 v[92:95], v90 offset:32784
	v_lshlrev_b32_e32 v32, 16, v30
	v_and_b32_e32 v30, 0xffff0000, v30
	s_waitcnt lgkmcnt(1)
	v_pk_fma_f32 v[74:75], v[74:75], v[110:111], v[28:29]
	v_lshlrev_b32_e32 v28, 16, v31
	v_and_b32_e32 v29, 0xffff0000, v31
	v_sub_f32_e32 v31, v30, v44
	v_sub_f32_e32 v30, v32, v44
	v_sub_f32_e32 v29, v29, v44
	v_sub_f32_e32 v28, v28, v44
	v_pk_mul_f32 v[30:31], v[44:45], v[30:31] op_sel:[1,0]
	v_pk_mul_f32 v[28:29], v[44:45], v[28:29] op_sel:[1,0]
	v_pk_fma_f32 v[30:31], v[30:31], v[100:101], v[104:105]
	v_pk_fma_f32 v[28:29], v[28:29], v[102:103], v[106:107]
	v_pk_mul_f32 v[30:31], v[30:31], s[16:17] op_sel_hi:[1,0]
	v_pk_fma_f32 v[76:77], v[76:77], v[108:109], v[96:97]
	v_pk_mul_f32 v[28:29], v[28:29], s[16:17] op_sel_hi:[1,0]
	s_waitcnt lgkmcnt(0)
	v_pk_fma_f32 v[30:31], v[70:71], v[92:93], v[30:31]
	v_pk_fma_f32 v[28:29], v[72:73], v[94:95], v[28:29]
	v_mov_b32_e32 v70, v76
	v_mov_b32_e32 v71, v30
	v_mov_b32_e32 v72, v77
	v_mov_b32_e32 v73, v31
	v_pk_add_f32 v[70:71], v[70:71], v[72:73]
	v_mov_b32_e32 v72, v74
	v_mov_b32_e32 v73, v28
	v_mov_b32_e32 v92, v75
	v_mov_b32_e32 v93, v29
	v_pk_add_f32 v[72:73], v[72:73], v[92:93]
	s_ashr_i32 s23, s22, 31
	v_pk_add_f32 v[70:71], v[70:71], v[72:73]
	s_lshl_b64 s[22:23], s[22:23], 12
	v_add_f32_e32 v32, 0, v70
	v_add_f32_e32 v108, v32, v71
	v_lshlrev_b32_e32 v70, 16, v25
	v_and_b32_e32 v71, 0xffff0000, v25
	v_sub_f32_e32 v97, v71, v44
	v_sub_f32_e32 v96, v70, v44
	ds_read_b128 v[70:73], v87 offset:2048
	ds_read_b128 v[92:95], v87 offset:10240
	v_lshlrev_b32_e32 v32, 16, v24
	v_and_b32_e32 v24, 0xffff0000, v24
	v_pk_mul_f32 v[110:111], v[44:45], v[96:97] op_sel:[1,0]
	ds_read_b128 v[96:99], v87 offset:2064
	ds_read_b128 v[100:103], v87 offset:10256
	ds_read_b128 v[104:107], v90 offset:34816
	v_sub_f32_e32 v25, v24, v44
	v_sub_f32_e32 v24, v32, v44
	v_pk_mul_f32 v[24:25], v[44:45], v[24:25] op_sel:[1,0]
	v_lshlrev_b32_e32 v32, 16, v26
	s_waitcnt lgkmcnt(3)
	v_pk_fma_f32 v[24:25], v[24:25], v[70:71], v[92:93]
	v_pk_fma_f32 v[70:71], v[110:111], v[72:73], v[94:95]
	v_pk_mul_f32 v[24:25], v[24:25], s[16:17] op_sel_hi:[1,0]
	v_pk_mul_f32 v[92:93], v[70:71], s[16:17] op_sel_hi:[1,0]
	ds_read_b128 v[70:73], v90 offset:34832
	s_waitcnt lgkmcnt(1)
	v_pk_fma_f32 v[68:69], v[68:69], v[104:105], v[24:25]
	v_pk_fma_f32 v[66:67], v[66:67], v[106:107], v[92:93]
	v_mov_b32_e32 v92, v68
	v_pk_mov_b32 v[24:25], v[68:69], v[66:67] op_sel:[1,0]
	v_mov_b32_e32 v93, v67
	v_pk_add_f32 v[24:25], v[24:25], v[92:93]
	v_and_b32_e32 v26, 0xffff0000, v26
	v_pk_add_f32 v[104:105], v[24:25], v[24:25] op_sel:[0,1] op_sel_hi:[1,0]
	v_lshlrev_b32_e32 v24, 16, v27
	v_and_b32_e32 v25, 0xffff0000, v27
	v_sub_f32_e32 v27, v26, v44
	v_sub_f32_e32 v26, v32, v44
	v_sub_f32_e32 v25, v25, v44
	v_sub_f32_e32 v24, v24, v44
	v_pk_mul_f32 v[26:27], v[44:45], v[26:27] op_sel:[1,0]
	v_pk_mul_f32 v[24:25], v[44:45], v[24:25] op_sel:[1,0]
	v_pk_fma_f32 v[26:27], v[26:27], v[96:97], v[100:101]
	v_pk_fma_f32 v[24:25], v[24:25], v[98:99], v[102:103]
	v_pk_mul_f32 v[26:27], v[26:27], s[16:17] op_sel_hi:[1,0]
	v_pk_mul_f32 v[24:25], v[24:25], s[16:17] op_sel_hi:[1,0]
	s_waitcnt lgkmcnt(0)
	v_pk_fma_f32 v[26:27], v[62:63], v[70:71], v[26:27]
	v_and_b32_e32 v62, 0xffff0000, v20
	v_pk_fma_f32 v[24:25], v[64:65], v[72:73], v[24:25]
	v_lshlrev_b32_e32 v32, 16, v20
	v_sub_f32_e32 v93, v62, v44
	ds_read_b128 v[62:65], v87 offset:4096
	ds_read_b128 v[70:73], v87 offset:12288
	v_sub_f32_e32 v92, v32, v44
	v_lshlrev_b32_e32 v20, 16, v21
	v_and_b32_e32 v21, 0xffff0000, v21
	v_pk_mul_f32 v[112:113], v[44:45], v[92:93] op_sel:[1,0]
	ds_read_b128 v[92:95], v87 offset:4112
	ds_read_b128 v[96:99], v87 offset:12304
	ds_read_b128 v[100:103], v90 offset:36864
	v_sub_f32_e32 v21, v21, v44
	v_sub_f32_e32 v20, v20, v44
	v_pk_mul_f32 v[20:21], v[44:45], v[20:21] op_sel:[1,0]
	s_waitcnt lgkmcnt(3)
	v_pk_fma_f32 v[62:63], v[112:113], v[62:63], v[70:71]
	v_pk_fma_f32 v[20:21], v[20:21], v[64:65], v[72:73]
	v_pk_mul_f32 v[70:71], v[62:63], s[16:17] op_sel_hi:[1,0]
	v_pk_mul_f32 v[20:21], v[20:21], s[16:17] op_sel_hi:[1,0]
	ds_read_b128 v[62:65], v90 offset:36880
	s_waitcnt lgkmcnt(1)
	v_pk_fma_f32 v[60:61], v[60:61], v[102:103], v[20:21]
	v_pk_fma_f32 v[58:59], v[58:59], v[100:101], v[70:71]
	v_add_f32_e32 v106, v26, v27
	v_add_f32_e32 v110, v24, v25
	v_mov_b32_e32 v109, v58
	v_mov_b32_e32 v105, v59
	v_mov_b32_e32 v107, v60
	v_mov_b32_e32 v111, v61
	v_pk_add_f32 v[20:21], v[108:109], v[104:105]
	v_pk_add_f32 v[70:71], v[106:107], v[110:111]
	v_lshlrev_b32_e32 v32, 16, v16
	v_pk_add_f32 v[20:21], v[20:21], v[70:71]
	v_sub_f32_e32 v70, v32, v44
	v_pk_add_f32 v[100:101], v[20:21], v[20:21] op_sel:[0,1] op_sel_hi:[1,0]
	v_lshlrev_b32_e32 v20, 16, v22
	v_and_b32_e32 v21, 0xffff0000, v22
	v_lshlrev_b32_e32 v22, 16, v23
	v_and_b32_e32 v23, 0xffff0000, v23
	v_sub_f32_e32 v21, v21, v44
	v_sub_f32_e32 v20, v20, v44
	v_sub_f32_e32 v23, v23, v44
	v_sub_f32_e32 v22, v22, v44
	v_pk_mul_f32 v[22:23], v[44:45], v[22:23] op_sel:[1,0]
	v_pk_mul_f32 v[20:21], v[44:45], v[20:21] op_sel:[1,0]
	v_pk_fma_f32 v[22:23], v[22:23], v[94:95], v[98:99]
	v_pk_fma_f32 v[20:21], v[20:21], v[92:93], v[96:97]
	v_pk_mul_f32 v[22:23], v[22:23], s[16:17] op_sel_hi:[1,0]
	v_pk_mul_f32 v[20:21], v[20:21], s[16:17] op_sel_hi:[1,0]
	s_waitcnt lgkmcnt(0)
	v_pk_fma_f32 v[22:23], v[54:55], v[64:65], v[22:23]
	v_pk_fma_f32 v[20:21], v[56:57], v[62:63], v[20:21]
	v_mov_b32_e32 v57, v23
	v_pk_mov_b32 v[54:55], v[20:21], v[22:23] op_sel:[1,0]
	v_mov_b32_e32 v56, v20
	v_pk_add_f32 v[54:55], v[54:55], v[56:57]
	v_lshlrev_b32_e32 v32, 16, v18
	v_pk_add_f32 v[102:103], v[54:55], v[54:55] op_sel:[0,1] op_sel_hi:[1,0]
	v_and_b32_e32 v54, 0xffff0000, v16
	v_sub_f32_e32 v71, v54, v44
	ds_read_b128 v[54:57], v87 offset:6144
	ds_read_b128 v[62:65], v87 offset:14336
	v_lshlrev_b32_e32 v16, 16, v17
	v_and_b32_e32 v17, 0xffff0000, v17
	v_pk_mul_f32 v[104:105], v[44:45], v[70:71] op_sel:[1,0]
	ds_read_b128 v[70:73], v87 offset:6160
	ds_read_b128 v[92:95], v87 offset:14352
	ds_read_b128 v[96:99], v90 offset:38912
	v_sub_f32_e32 v17, v17, v44
	v_sub_f32_e32 v16, v16, v44
	v_pk_mul_f32 v[16:17], v[44:45], v[16:17] op_sel:[1,0]
	s_waitcnt lgkmcnt(3)
	v_pk_fma_f32 v[54:55], v[104:105], v[54:55], v[62:63]
	v_pk_fma_f32 v[16:17], v[16:17], v[56:57], v[64:65]
	v_pk_mul_f32 v[62:63], v[54:55], s[16:17] op_sel_hi:[1,0]
	v_pk_mul_f32 v[16:17], v[16:17], s[16:17] op_sel_hi:[1,0]
	ds_read_b128 v[54:57], v90 offset:38928
	s_waitcnt lgkmcnt(1)
	v_pk_fma_f32 v[52:53], v[52:53], v[98:99], v[16:17]
	v_and_b32_e32 v18, 0xffff0000, v18
	v_lshlrev_b32_e32 v16, 16, v19
	v_and_b32_e32 v17, 0xffff0000, v19
	v_sub_f32_e32 v17, v17, v44
	v_sub_f32_e32 v16, v16, v44
	v_sub_f32_e32 v19, v18, v44
	v_sub_f32_e32 v18, v32, v44
	v_pk_mul_f32 v[18:19], v[44:45], v[18:19] op_sel:[1,0]
	v_pk_mul_f32 v[16:17], v[44:45], v[16:17] op_sel:[1,0]
	v_pk_fma_f32 v[18:19], v[18:19], v[70:71], v[92:93]
	v_pk_fma_f32 v[16:17], v[16:17], v[72:73], v[94:95]
	v_pk_mul_f32 v[18:19], v[18:19], s[16:17] op_sel_hi:[1,0]
	v_pk_mul_f32 v[16:17], v[16:17], s[16:17] op_sel_hi:[1,0]
	v_pk_fma_f32 v[50:51], v[50:51], v[96:97], v[62:63]
	s_waitcnt lgkmcnt(0)
	v_pk_fma_f32 v[16:17], v[48:49], v[56:57], v[16:17]
	v_pk_fma_f32 v[18:19], v[46:47], v[54:55], v[18:19]
	v_add_f32_e32 v62, v50, v51
	v_add_f32_e32 v64, v52, v53
	v_mov_b32_e32 v101, v18
	v_mov_b32_e32 v103, v19
	v_mov_b32_e32 v63, v16
	v_mov_b32_e32 v65, v17
	v_pk_add_f32 v[44:45], v[100:101], v[102:103]
	v_pk_add_f32 v[46:47], v[62:63], v[64:65]
	v_mov_b32_e32 v91, v89
	v_pk_add_f32 v[44:45], v[44:45], v[46:47]
	s_nop 0
	v_add_f32_e32 v32, v44, v45
	ds_bpermute_b32 v44, v81, v32
	s_waitcnt lgkmcnt(0)
	v_add_f32_e32 v32, v32, v44
	ds_bpermute_b32 v44, v82, v32
	s_waitcnt lgkmcnt(0)
	v_add_f32_e32 v32, v32, v44
	ds_bpermute_b32 v44, v83, v32
	s_waitcnt lgkmcnt(0)
	v_add_f32_e32 v32, v32, v44
	ds_bpermute_b32 v44, v84, v32
	s_waitcnt lgkmcnt(0)
	v_add_f32_e32 v32, v32, v44
	ds_bpermute_b32 v44, v85, v32
	s_waitcnt lgkmcnt(0)
	v_add_f32_e32 v32, v32, v44
	ds_bpermute_b32 v44, v86, v32
	s_waitcnt lgkmcnt(0)
	v_add_f32_e32 v56, v32, v44
	v_fmamk_f32 v77, v56, 0xba000000, v77
	v_fmamk_f32 v31, v56, 0xba000000, v31
	v_fmamk_f32 v75, v56, 0xba000000, v75
	v_fmac_f32_e32 v76, 0xba000000, v56
	v_fmamk_f32 v29, v56, 0xba000000, v29
	v_fmac_f32_e32 v30, 0xba000000, v56
	v_mov_b32_e32 v46, v77
	v_mov_b32_e32 v47, v31
	v_fmac_f32_e32 v74, 0xba000000, v56
	v_fmac_f32_e32 v28, 0xba000000, v56
	v_mov_b32_e32 v44, v76
	v_mov_b32_e32 v45, v30
	v_pk_mul_f32 v[46:47], v[46:47], v[46:47]
	v_mov_b32_e32 v48, v75
	v_mov_b32_e32 v49, v29
	v_pk_fma_f32 v[44:45], v[44:45], v[44:45], v[46:47]
	v_mov_b32_e32 v46, v74
	v_mov_b32_e32 v47, v28
	v_pk_mul_f32 v[48:49], v[48:49], v[48:49]
	v_fmamk_f32 v69, v56, 0xba000000, v69
	v_pk_fma_f32 v[46:47], v[46:47], v[46:47], v[48:49]
	v_fmac_f32_e32 v68, 0xba000000, v56
	v_fmamk_f32 v67, v56, 0xba000000, v67
	v_fmac_f32_e32 v66, 0xba000000, v56
	v_pk_add_f32 v[44:45], v[44:45], v[46:47]
	v_pk_mul_f32 v[46:47], v[66:67], v[66:67]
	v_pk_mul_f32 v[48:49], v[68:69], v[68:69]
	v_fmac_f32_e32 v26, 0xba000000, v56
	v_pk_mov_b32 v[54:55], v[48:49], v[46:47] op_sel:[1,0]
	v_mov_b32_e32 v49, v47
	v_fmamk_f32 v27, v56, 0xba000000, v27
	v_fmac_f32_e32 v24, 0xba000000, v56
	v_mul_f32_e32 v32, v26, v26
	v_pk_add_f32 v[46:47], v[54:55], v[48:49]
	v_fmamk_f32 v25, v56, 0xba000000, v25
	v_pk_fma_f32 v[48:49], v[26:27], v[26:27], v[32:33] op_sel_hi:[1,1,0]
	v_mul_f32_e32 v32, v24, v24
	v_pk_add_f32 v[44:45], v[44:45], v[44:45] op_sel_hi:[0,1]
	v_pk_add_f32 v[46:47], v[46:47], v[46:47] op_sel_hi:[0,1]
	v_pk_fma_f32 v[54:55], v[24:25], v[24:25], v[32:33] op_sel_hi:[1,1,0]
	v_fmamk_f32 v61, v56, 0xba000000, v61
	v_fmac_f32_e32 v60, 0xba000000, v56
	v_fmamk_f32 v59, v56, 0xba000000, v59
	v_fmac_f32_e32 v58, 0xba000000, v56
	v_mul_f32_e32 v48, v58, v58
	v_mul_f32_e32 v54, v59, v59
	v_mul_f32_e32 v46, v60, v60
	v_mul_f32_e32 v44, v61, v61
	v_pk_add_f32 v[48:49], v[48:49], v[54:55]
	v_pk_add_f32 v[44:45], v[46:47], v[44:45]
	v_fmamk_f32 v21, v56, 0xba000000, v21
	v_fmac_f32_e32 v20, 0xba000000, v56
	v_fmamk_f32 v23, v56, 0xba000000, v23
	v_fmac_f32_e32 v22, 0xba000000, v56
	v_pk_add_f32 v[44:45], v[48:49], v[44:45]
	v_pk_mul_f32 v[46:47], v[22:23], v[22:23]
	v_pk_mul_f32 v[48:49], v[20:21], v[20:21]
	v_fmac_f32_e32 v50, 0xba000000, v56
	v_pk_mov_b32 v[54:55], v[48:49], v[46:47] op_sel:[1,0]
	v_mov_b32_e32 v49, v47
	v_fmamk_f32 v51, v56, 0xba000000, v51
	v_fmac_f32_e32 v52, 0xba000000, v56
	v_mul_f32_e32 v32, v50, v50
	v_pk_add_f32 v[46:47], v[54:55], v[48:49]
	v_fmamk_f32 v53, v56, 0xba000000, v53
	v_pk_fma_f32 v[48:49], v[50:51], v[50:51], v[32:33] op_sel_hi:[1,1,0]
	v_mul_f32_e32 v32, v52, v52
	v_pk_add_f32 v[44:45], v[44:45], v[44:45] op_sel_hi:[0,1]
	v_pk_add_f32 v[46:47], v[46:47], v[46:47] op_sel_hi:[0,1]
	v_pk_fma_f32 v[54:55], v[52:53], v[52:53], v[32:33] op_sel_hi:[1,1,0]
	v_fmamk_f32 v17, v56, 0xba000000, v17
	v_fmac_f32_e32 v16, 0xba000000, v56
	v_fmamk_f32 v19, v56, 0xba000000, v19
	v_fmac_f32_e32 v18, 0xba000000, v56
	v_mul_f32_e32 v48, v18, v18
	v_mul_f32_e32 v54, v19, v19
	v_mul_f32_e32 v46, v16, v16
	v_mul_f32_e32 v44, v17, v17
	v_pk_add_f32 v[48:49], v[48:49], v[54:55]
	v_pk_add_f32 v[44:45], v[46:47], v[44:45]
	s_nop 0
	v_pk_add_f32 v[44:45], v[48:49], v[44:45]
	s_nop 0
	v_add_f32_e32 v32, v44, v45
	ds_bpermute_b32 v44, v81, v32
	s_waitcnt lgkmcnt(0)
	v_add_f32_e32 v32, v32, v44
	ds_bpermute_b32 v44, v82, v32
	s_waitcnt lgkmcnt(0)
	v_add_f32_e32 v32, v32, v44
	ds_bpermute_b32 v44, v83, v32
	s_waitcnt lgkmcnt(0)
	v_add_f32_e32 v32, v32, v44
	ds_bpermute_b32 v44, v84, v32
	s_waitcnt lgkmcnt(0)
	v_add_f32_e32 v32, v32, v44
	ds_bpermute_b32 v44, v85, v32
	s_waitcnt lgkmcnt(0)
	v_add_f32_e32 v32, v32, v44
	ds_bpermute_b32 v44, v86, v32
	s_waitcnt lgkmcnt(0)
	v_add_f32_e32 v32, v32, v44
	v_fmamk_f32 v32, v32, 0x3a000000, v88
	v_mul_f32_e32 v44, 0x4b800000, v32
	v_cmp_gt_f32_e32 vcc, s17, v32
	s_nop 1
	v_cndmask_b32_e32 v32, v32, v44, vcc
	v_rsq_f32_e32 v32, v32
	s_nop 0
	v_mul_f32_e32 v44, 0x45800000, v32
	v_cndmask_b32_e32 v32, v32, v44, vcc
	ds_read_b128 v[44:47], v87 offset:16384
	ds_read_b128 v[54:57], v87 offset:24576
	v_pk_mul_f32 v[48:49], v[76:77], v[32:33] op_sel_hi:[1,0]
	v_pk_mul_f32 v[74:75], v[74:75], v[32:33] op_sel_hi:[1,0]
	ds_read_b128 v[62:65], v87 offset:16400
	ds_read_b128 v[70:73], v87 offset:24592
	v_pk_mul_f32 v[30:31], v[30:31], v[32:33] op_sel_hi:[1,0]
	s_waitcnt lgkmcnt(2)
	v_pk_fma_f32 v[96:97], v[46:47], v[74:75], v[56:57]
	v_pk_fma_f32 v[48:49], v[44:45], v[48:49], v[54:55]
	ds_read_b128 v[54:57], v90 offset:49152
	ds_read_b128 v[74:77], v90 offset:40960
	ds_read_b128 v[92:95], v90 offset:49168
	v_pk_mul_f32 v[28:29], v[28:29], v[32:33] op_sel_hi:[1,0]
	s_waitcnt lgkmcnt(3)
	v_pk_fma_f32 v[30:31], v[62:63], v[30:31], v[70:71]
	v_pk_fma_f32 v[28:29], v[64:65], v[28:29], v[72:73]
	s_waitcnt lgkmcnt(2)
	v_pk_add_f32 v[98:99], v[56:57], 1.0 op_sel_hi:[1,0]
	v_pk_add_f32 v[100:101], v[54:55], 1.0 op_sel_hi:[1,0]
	ds_read_b128 v[54:57], v90 offset:40976
	v_cvt_pk_bf16_f32 v46, v48, v49
	v_cvt_pk_bf16_f32 v47, v96, v97
	v_lshl_add_u64 v[44:45], v[38:39], 0, s[22:23]
	s_waitcnt lgkmcnt(2)
	v_pk_fma_f32 v[74:75], v[100:101], v[48:49], v[74:75]
	v_cvt_pk_bf16_f32 v48, v30, v31
	v_cvt_pk_bf16_f32 v49, v28, v29
	global_store_dwordx4 v[44:45], v[46:49], off
	v_pk_fma_f32 v[76:77], v[98:99], v[96:97], v[76:77]
	v_pk_mul_f32 v[68:69], v[68:69], v[32:33] op_sel_hi:[1,0]
	s_waitcnt lgkmcnt(1)
	v_pk_add_f32 v[46:47], v[94:95], 1.0 op_sel_hi:[1,0]
	v_pk_add_f32 v[48:49], v[92:93], 1.0 op_sel_hi:[1,0]
	s_waitcnt lgkmcnt(0)
	v_pk_fma_f32 v[46:47], v[46:47], v[28:29], v[56:57]
	v_pk_fma_f32 v[30:31], v[48:49], v[30:31], v[54:55]
	v_cvt_pk_bf16_f32 v28, v74, v75
	v_cvt_pk_bf16_f32 v29, v76, v77
	v_cvt_pk_bf16_f32 v30, v30, v31
	v_cvt_pk_bf16_f32 v31, v46, v47
	v_lshl_add_u64 v[74:75], v[40:41], 0, s[22:23]
	global_store_dwordx4 v[74:75], v[28:31], off
	ds_read_b128 v[28:31], v87 offset:18432
	ds_read_b128 v[46:49], v87 offset:26624
	v_pk_mul_f32 v[66:67], v[66:67], v[32:33] op_sel_hi:[1,0]
	ds_read_b128 v[54:57], v87 offset:18448
	ds_read_b128 v[62:65], v87 offset:26640
	v_pk_mul_f32 v[26:27], v[26:27], v[32:33] op_sel_hi:[1,0]
	v_pk_mul_f32 v[24:25], v[24:25], v[32:33] op_sel_hi:[1,0]
	s_waitcnt lgkmcnt(2)
	v_pk_fma_f32 v[48:49], v[30:31], v[66:67], v[48:49]
	v_pk_fma_f32 v[76:77], v[28:29], v[68:69], v[46:47]
	ds_read_b128 v[28:31], v90 offset:51200
	ds_read_b128 v[66:69], v90 offset:43008
	ds_read_b128 v[70:73], v90 offset:51216
	s_waitcnt lgkmcnt(3)
	v_pk_fma_f32 v[24:25], v[56:57], v[24:25], v[64:65]
	v_pk_fma_f32 v[26:27], v[54:55], v[26:27], v[62:63]
	v_cvt_pk_bf16_f32 v46, v76, v77
	s_waitcnt lgkmcnt(2)
	v_pk_add_f32 v[92:93], v[30:31], 1.0 op_sel_hi:[1,0]
	v_pk_add_f32 v[94:95], v[28:29], 1.0 op_sel_hi:[1,0]
	ds_read_b128 v[28:31], v90 offset:43024
	v_cvt_pk_bf16_f32 v47, v48, v49
	s_waitcnt lgkmcnt(2)
	v_pk_fma_f32 v[68:69], v[92:93], v[48:49], v[68:69]
	v_cvt_pk_bf16_f32 v48, v26, v27
	v_cvt_pk_bf16_f32 v49, v24, v25
	global_store_dwordx4 v[44:45], v[46:49], off offset:1024
	v_pk_fma_f32 v[66:67], v[94:95], v[76:77], v[66:67]
	v_pk_mul_f32 v[58:59], v[58:59], v[32:33] op_sel_hi:[1,0]
	s_waitcnt lgkmcnt(1)
	v_pk_add_f32 v[46:47], v[72:73], 1.0 op_sel_hi:[1,0]
	v_pk_add_f32 v[48:49], v[70:71], 1.0 op_sel_hi:[1,0]
	s_waitcnt lgkmcnt(0)
	v_pk_fma_f32 v[30:31], v[46:47], v[24:25], v[30:31]
	v_pk_fma_f32 v[26:27], v[48:49], v[26:27], v[28:29]
	v_cvt_pk_bf16_f32 v24, v66, v67
	v_cvt_pk_bf16_f32 v25, v68, v69
	v_cvt_pk_bf16_f32 v26, v26, v27
	v_cvt_pk_bf16_f32 v27, v30, v31
	global_store_dwordx4 v[74:75], v[24:27], off offset:1024
	ds_read_b128 v[24:27], v87 offset:20480
	ds_read_b128 v[28:31], v87 offset:28672
	v_pk_mul_f32 v[60:61], v[60:61], v[32:33] op_sel_hi:[1,0]
	ds_read_b128 v[46:49], v87 offset:20496
	ds_read_b128 v[54:57], v87 offset:28688
	v_pk_mul_f32 v[20:21], v[20:21], v[32:33] op_sel_hi:[1,0]
	v_pk_mul_f32 v[22:23], v[22:23], v[32:33] op_sel_hi:[1,0]
	s_waitcnt lgkmcnt(2)
	v_pk_fma_f32 v[30:31], v[26:27], v[60:61], v[30:31]
	v_pk_fma_f32 v[66:67], v[24:25], v[58:59], v[28:29]
	ds_read_b128 v[24:27], v90 offset:53248
	ds_read_b128 v[58:61], v90 offset:45056
	ds_read_b128 v[62:65], v90 offset:53264
	s_waitcnt lgkmcnt(3)
	v_pk_fma_f32 v[22:23], v[48:49], v[22:23], v[56:57]
	v_pk_fma_f32 v[20:21], v[46:47], v[20:21], v[54:55]
	v_cvt_pk_bf16_f32 v28, v66, v67
	s_waitcnt lgkmcnt(2)
	v_pk_add_f32 v[68:69], v[26:27], 1.0 op_sel_hi:[1,0]
	v_pk_add_f32 v[70:71], v[24:25], 1.0 op_sel_hi:[1,0]
	ds_read_b128 v[24:27], v90 offset:45072
	v_cvt_pk_bf16_f32 v29, v30, v31
	s_waitcnt lgkmcnt(2)
	v_pk_fma_f32 v[60:61], v[68:69], v[30:31], v[60:61]
	v_cvt_pk_bf16_f32 v30, v20, v21
	v_cvt_pk_bf16_f32 v31, v22, v23
	global_store_dwordx4 v[44:45], v[28:31], off offset:2048
	v_pk_fma_f32 v[58:59], v[70:71], v[66:67], v[58:59]
	v_pk_mul_f32 v[50:51], v[50:51], v[32:33] op_sel_hi:[1,0]
	s_waitcnt lgkmcnt(1)
	v_pk_add_f32 v[28:29], v[64:65], 1.0 op_sel_hi:[1,0]
	v_pk_add_f32 v[30:31], v[62:63], 1.0 op_sel_hi:[1,0]
	s_waitcnt lgkmcnt(0)
	v_pk_fma_f32 v[26:27], v[28:29], v[22:23], v[26:27]
	v_pk_fma_f32 v[22:23], v[30:31], v[20:21], v[24:25]
	v_cvt_pk_bf16_f32 v20, v58, v59
	v_cvt_pk_bf16_f32 v21, v60, v61
	v_cvt_pk_bf16_f32 v22, v22, v23
	v_cvt_pk_bf16_f32 v23, v26, v27
	global_store_dwordx4 v[74:75], v[20:23], off offset:2048
	ds_read_b128 v[20:23], v87 offset:22528
	ds_read_b128 v[24:27], v87 offset:30720
	v_pk_mul_f32 v[52:53], v[52:53], v[32:33] op_sel_hi:[1,0]
	ds_read_b128 v[28:31], v87 offset:22544
	ds_read_b128 v[46:49], v87 offset:30736
	v_pk_mul_f32 v[18:19], v[18:19], v[32:33] op_sel_hi:[1,0]
	v_pk_mul_f32 v[16:17], v[16:17], v[32:33] op_sel_hi:[1,0]
	s_waitcnt lgkmcnt(2)
	v_pk_fma_f32 v[26:27], v[52:53], v[22:23], v[26:27]
	v_pk_fma_f32 v[58:59], v[50:51], v[20:21], v[24:25]
	ds_read_b128 v[20:23], v90 offset:55296
	ds_read_b128 v[50:53], v90 offset:47104
	ds_read_b128 v[54:57], v90 offset:55312
	s_waitcnt lgkmcnt(3)
	v_pk_fma_f32 v[16:17], v[16:17], v[30:31], v[48:49]
	v_pk_fma_f32 v[18:19], v[18:19], v[28:29], v[46:47]
	v_cvt_pk_bf16_f32 v24, v58, v59
	s_waitcnt lgkmcnt(2)
	v_pk_add_f32 v[60:61], v[22:23], 1.0 op_sel_hi:[1,0]
	v_pk_add_f32 v[62:63], v[20:21], 1.0 op_sel_hi:[1,0]
	ds_read_b128 v[20:23], v90 offset:47120
	v_cvt_pk_bf16_f32 v25, v26, v27
	s_waitcnt lgkmcnt(2)
	v_pk_fma_f32 v[52:53], v[26:27], v[60:61], v[52:53]
	v_cvt_pk_bf16_f32 v26, v18, v19
	v_cvt_pk_bf16_f32 v27, v16, v17
	global_store_dwordx4 v[44:45], v[24:27], off offset:3072
	v_pk_fma_f32 v[50:51], v[58:59], v[62:63], v[50:51]
	v_mov_b64_e32 v[30:31], v[2:3]
	s_waitcnt lgkmcnt(1)
	v_pk_add_f32 v[24:25], v[56:57], 1.0 op_sel_hi:[1,0]
	v_pk_add_f32 v[26:27], v[54:55], 1.0 op_sel_hi:[1,0]
	s_waitcnt lgkmcnt(0)
	v_pk_fma_f32 v[22:23], v[16:17], v[24:25], v[22:23]
	v_pk_fma_f32 v[18:19], v[18:19], v[26:27], v[20:21]
	v_cvt_pk_bf16_f32 v16, v50, v51
	v_cvt_pk_bf16_f32 v17, v52, v53
	v_cvt_pk_bf16_f32 v18, v18, v19
	v_cvt_pk_bf16_f32 v19, v22, v23
	global_store_dwordx4 v[74:75], v[16:19], off offset:3072
	v_mov_b64_e32 v[26:27], v[6:7]
	v_mov_b64_e32 v[22:23], v[10:11]
	v_mov_b64_e32 v[18:19], v[14:15]
	s_and_b64 vcc, exec, s[20:21]
	v_mov_b64_e32 v[28:29], v[0:1]
	v_mov_b64_e32 v[24:25], v[4:5]
	v_mov_b64_e32 v[20:21], v[8:9]
	v_mov_b64_e32 v[16:17], v[12:13]
	v_mov_b32_e32 v90, v79
	v_mov_b64_e32 v[44:45], v[42:43]
	s_mov_b32 s22, s18
	s_cbranch_vccnz .LBB0_1849

.LBB0_1844:
	s_waitcnt vmcnt(2)
	v_cmp_lt_i32_e32 vcc, -1, v90
	s_and_b32 s14, vcc_lo, 0xffff
	s_cmp_eq_u64 s[14:15], 0
	s_cbranch_scc1 .LBB0_1838
	v_mov_b32_e32 v76, 0
	s_mov_b64 s[24:25], s[14:15]
	v_mov_b32_e32 v77, v76
	v_mov_b32_e32 v74, v76
	v_mov_b32_e32 v75, v76
	v_mov_b32_e32 v70, v76
	v_mov_b32_e32 v71, v76
	v_mov_b32_e32 v72, v76
	v_mov_b32_e32 v73, v76
	v_mov_b32_e32 v68, v76
	v_mov_b32_e32 v69, v76
	v_mov_b32_e32 v66, v76
	v_mov_b32_e32 v67, v76
	v_mov_b32_e32 v62, v76
	v_mov_b32_e32 v63, v76
	v_mov_b32_e32 v64, v76
	v_mov_b32_e32 v65, v76
	v_mov_b32_e32 v58, v76
	v_mov_b32_e32 v59, v76
	v_mov_b32_e32 v60, v76
	v_mov_b32_e32 v61, v76
	v_mov_b32_e32 v56, v76
	v_mov_b32_e32 v57, v76
	v_mov_b32_e32 v54, v76
	v_mov_b32_e32 v55, v76
	v_mov_b32_e32 v50, v76
	v_mov_b32_e32 v51, v76
	v_mov_b32_e32 v52, v76
	v_mov_b32_e32 v53, v76
	v_mov_b32_e32 v46, v76
	v_mov_b32_e32 v47, v76
	v_mov_b32_e32 v48, v76
	v_mov_b32_e32 v49, v76
	s_cmp_eq_u32 s98, 0
	s_cbranch_scc1 .LBB0_1847
	v_mov_b32_e32 v92, v216
	v_mov_b32_e32 v32, v217
	v_mov_b32_e32 v93, v217
	v_cvt_pk_f32_fp8_e32 v[116:117], v202
	v_cvt_pk_f32_fp8_sdwa v[118:119], v202 src0_sel:WORD_1
	v_cvt_pk_f32_fp8_e32 v[120:121], v203
	v_cvt_pk_f32_fp8_sdwa v[202:203], v203 src0_sel:WORD_1
	v_cvt_pk_f32_fp8_e32 v[128:129], v206
	v_cvt_pk_f32_fp8_e32 v[146:147], v212
	v_cvt_pk_f32_fp8_sdwa v[148:149], v212 src0_sel:WORD_1
	v_cvt_pk_f32_fp8_e32 v[150:151], v213
	v_cvt_pk_f32_fp8_sdwa v[212:213], v213 src0_sel:WORD_1
	v_cvt_pk_f32_fp8_e32 v[152:153], v214
	v_cvt_pk_f32_fp8_sdwa v[154:155], v214 src0_sel:WORD_1
	v_cvt_pk_f32_fp8_e32 v[156:157], v215
	v_cvt_pk_f32_fp8_sdwa v[214:215], v215 src0_sel:WORD_1
	v_cvt_pk_f32_fp8_sdwa v[130:131], v206 src0_sel:WORD_1
	v_cvt_pk_f32_fp8_e32 v[132:133], v207
	v_cvt_pk_f32_fp8_sdwa v[206:207], v207 src0_sel:WORD_1
	v_cvt_pk_f32_fp8_e32 v[140:141], v210
	v_cvt_pk_f32_fp8_sdwa v[142:143], v210 src0_sel:WORD_1
	v_cvt_pk_f32_fp8_e32 v[144:145], v211
	v_cvt_pk_f32_fp8_sdwa v[210:211], v211 src0_sel:WORD_1
	v_cvt_pk_f32_fp8_e32 v[94:95], v200
	v_cvt_pk_f32_fp8_sdwa v[96:97], v200 src0_sel:WORD_1
	v_cvt_pk_f32_fp8_e32 v[114:115], v201
	v_cvt_pk_f32_fp8_sdwa v[200:201], v201 src0_sel:WORD_1
	v_cvt_pk_f32_fp8_e32 v[122:123], v204
	v_cvt_pk_f32_fp8_sdwa v[124:125], v204 src0_sel:WORD_1
	v_cvt_pk_f32_fp8_e32 v[126:127], v205
	v_cvt_pk_f32_fp8_sdwa v[204:205], v205 src0_sel:WORD_1
	v_cvt_pk_f32_fp8_e32 v[134:135], v208
	v_cvt_pk_f32_fp8_sdwa v[136:137], v208 src0_sel:WORD_1
	v_cvt_pk_f32_fp8_e32 v[138:139], v209
	v_cvt_pk_f32_fp8_sdwa v[208:209], v209 src0_sel:WORD_1
	v_mul_f32_e32 v158, v32, v214
	v_mov_b32_e32 v214, v213
	v_pk_mul_f32 v[116:117], v[32:33], v[116:117] op_sel_hi:[0,1]
	v_pk_mul_f32 v[118:119], v[32:33], v[118:119] op_sel_hi:[0,1]
	v_pk_mul_f32 v[120:121], v[32:33], v[120:121] op_sel_hi:[0,1]
	v_pk_mul_f32 v[202:203], v[32:33], v[202:203] op_sel_hi:[0,1]
	v_pk_mul_f32 v[128:129], v[32:33], v[128:129] op_sel_hi:[0,1]
	v_pk_mul_f32 v[130:131], v[32:33], v[130:131] op_sel_hi:[0,1]
	v_pk_mul_f32 v[132:133], v[32:33], v[132:133] op_sel_hi:[0,1]
	v_pk_mul_f32 v[206:207], v[32:33], v[206:207] op_sel_hi:[0,1]
	v_pk_mul_f32 v[140:141], v[32:33], v[140:141] op_sel_hi:[0,1]
	v_pk_mul_f32 v[142:143], v[32:33], v[142:143] op_sel_hi:[0,1]
	v_pk_mul_f32 v[144:145], v[32:33], v[144:145] op_sel_hi:[0,1]
	v_pk_mul_f32 v[210:211], v[32:33], v[210:211] op_sel_hi:[0,1]
	v_pk_mul_f32 v[152:153], v[32:33], v[152:153] op_sel_hi:[0,1]
	v_pk_mul_f32 v[154:155], v[32:33], v[154:155] op_sel_hi:[0,1]
	v_pk_mul_f32 v[156:157], v[32:33], v[156:157] op_sel_hi:[0,1]
	v_pk_mul_f32 v[214:215], v[92:93], v[214:215]
	v_mul_f32_e32 v212, v92, v212
	v_pk_fma_f32 v[94:95], v[92:93], v[94:95], v[116:117] op_sel_hi:[0,1,1]
	v_pk_fma_f32 v[96:97], v[92:93], v[96:97], v[118:119] op_sel_hi:[0,1,1]
	v_pk_fma_f32 v[114:115], v[92:93], v[114:115], v[120:121] op_sel_hi:[0,1,1]
	v_pk_fma_f32 v[200:201], v[92:93], v[200:201], v[202:203] op_sel_hi:[0,1,1]
	v_pk_fma_f32 v[202:203], v[92:93], v[122:123], v[128:129] op_sel_hi:[0,1,1]
	v_pk_fma_f32 v[116:117], v[92:93], v[124:125], v[130:131] op_sel_hi:[0,1,1]
	v_pk_fma_f32 v[118:119], v[92:93], v[126:127], v[132:133] op_sel_hi:[0,1,1]
	v_pk_fma_f32 v[204:205], v[92:93], v[204:205], v[206:207] op_sel_hi:[0,1,1]
	v_pk_fma_f32 v[206:207], v[92:93], v[134:135], v[140:141] op_sel_hi:[0,1,1]
	v_pk_fma_f32 v[120:121], v[92:93], v[136:137], v[142:143] op_sel_hi:[0,1,1]
	v_pk_fma_f32 v[122:123], v[92:93], v[138:139], v[144:145] op_sel_hi:[0,1,1]
	v_pk_fma_f32 v[208:209], v[92:93], v[208:209], v[210:211] op_sel_hi:[0,1,1]
	v_pk_fma_f32 v[210:211], v[92:93], v[146:147], v[152:153] op_sel_hi:[0,1,1]
	v_pk_fma_f32 v[124:125], v[92:93], v[148:149], v[154:155] op_sel_hi:[0,1,1]
	v_pk_fma_f32 v[92:93], v[92:93], v[150:151], v[156:157] op_sel_hi:[0,1,1]
	v_mov_b32_e32 v213, v214
	v_mov_b32_e32 v159, v215
	v_pk_add_f32 v[46:47], v[46:47], v[92:93]
	v_pk_add_f32 v[92:93], v[212:213], v[158:159]
	v_pk_add_f32 v[52:53], v[52:53], v[124:125]
	v_pk_add_f32 v[48:49], v[48:49], v[92:93]
	v_pk_add_f32 v[50:51], v[50:51], v[210:211]
	v_pk_add_f32 v[54:55], v[54:55], v[208:209]
	v_pk_add_f32 v[56:57], v[56:57], v[122:123]
	v_pk_add_f32 v[60:61], v[60:61], v[120:121]
	v_pk_add_f32 v[58:59], v[58:59], v[206:207]
	v_pk_add_f32 v[64:65], v[64:65], v[204:205]
	v_pk_add_f32 v[62:63], v[62:63], v[118:119]
	v_pk_add_f32 v[66:67], v[66:67], v[116:117]
	v_pk_add_f32 v[68:69], v[68:69], v[202:203]
	v_pk_add_f32 v[72:73], v[72:73], v[200:201]
	v_pk_add_f32 v[70:71], v[70:71], v[114:115]
	v_pk_add_f32 v[74:75], v[74:75], v[96:97]
	v_pk_add_f32 v[76:77], v[76:77], v[94:95]
	s_mov_b64 s[24:25], s[100:101]
	s_cmp_eq_u64 s[24:25], 0
	s_cbranch_scc1 .LBB0_1839
	s_branch .LBB0_1847

.LBB0_3050:
	s_or_b64 exec, exec, s[14:15]
	s_add_u32 s20, s6, 0x6fc18000
	s_addc_u32 s21, s7, 0
	s_lshl_b64 s[14:15], s[10:11], 3
	s_add_u32 s14, s20, s14
	s_addc_u32 s15, s21, s15
	global_load_dwordx2 v[50:51], v33, s[14:15]
	v_and_b32_e32 v86, 64, v4
	v_add_u32_e32 v0, 64, v86
	v_xor_b32_e32 v1, 1, v4
	v_cmp_lt_i32_e32 vcc, v1, v0
	v_mov_b32_e32 v94, 0x3727c5ac
	v_mov_b32_e32 v95, v33
	v_cndmask_b32_e32 v1, v4, v1, vcc
	v_lshlrev_b32_e32 v87, 2, v1
	v_xor_b32_e32 v1, 2, v4
	v_cmp_lt_i32_e32 vcc, v1, v0
	s_nop 1
	v_cndmask_b32_e32 v1, v4, v1, vcc
	v_lshlrev_b32_e32 v88, 2, v1
	v_xor_b32_e32 v1, 4, v4
	v_cmp_lt_i32_e32 vcc, v1, v0
	s_nop 1
	v_cndmask_b32_e32 v1, v4, v1, vcc
	v_lshlrev_b32_e32 v89, 2, v1
	v_xor_b32_e32 v1, 8, v4
	v_cmp_lt_i32_e32 vcc, v1, v0
	s_nop 1
	v_cndmask_b32_e32 v1, v4, v1, vcc
	v_lshlrev_b32_e32 v90, 2, v1
	v_xor_b32_e32 v1, 16, v4
	v_cmp_lt_i32_e32 vcc, v1, v0
	s_nop 1
	v_cndmask_b32_e32 v1, v4, v1, vcc
	v_lshlrev_b32_e32 v91, 2, v1
	v_xor_b32_e32 v1, 32, v4
	v_cmp_lt_i32_e32 vcc, v1, v0
	s_nop 1
	v_cndmask_b32_e32 v0, v4, v1, vcc
	v_lshlrev_b32_e32 v92, 2, v0
	v_lshlrev_b32_e32 v0, 1, v32
	v_mov_b32_e32 v1, v33
	v_lshl_add_u64 v[34:35], s[12:13], 0, v[0:1]
	v_lshl_add_u64 v[0:1], s[6:7], 0, v[32:33]
	s_mov_b64 s[6:7], 0x68358000
	v_lshlrev_b32_e32 v32, 2, v32
	v_lshl_add_u64 v[36:37], v[0:1], 0, s[6:7]
	v_or_b32_e32 v0, 0x1000, v32
	v_mov_b32_e32 v1, v33
	v_lshl_add_u64 v[40:41], s[4:5], 0, v[0:1]
	v_or_b32_e32 v0, 0x1010, v32
	s_mov_b32 s7, 0
	v_add_u32_e32 v93, 0, v32
	v_lshl_add_u64 v[38:39], s[4:5], 0, v[32:33]
	v_lshl_add_u64 v[42:43], s[4:5], 0, v[0:1]
	v_or_b32_e32 v0, 0x1800, v32
	v_or_b32_e32 v32, 0x1810, v32
	v_lshl_add_u64 v[44:45], s[4:5], 0, v[0:1]
	v_lshl_add_u64 v[46:47], s[4:5], 0, v[32:33]
	s_mov_b32 s5, 1.0
	s_mov_b32 s4, s7
	v_mov_b64_e32 v[48:49], s[4:5]
	s_mov_b32 s4, 0x3fb504f3
	s_mov_b32 s5, 0x800000
	s_mov_b32 s98, 0
	s_branch .LBB0_3053

.LBB0_3052:
	s_add_i32 s6, s10, 0xfffff000
	s_lshr_b32 s6, s6, 10
	s_add_i32 s6, s6, 1
	s_cmpk_gt_i32 s10, 0xfff
	s_cselect_b32 s6, s6, 0
	s_sub_i32 s6, s6, s18
	v_and_b32_e32 v96, 0xffff0000, v28
	s_mulk_i32 s6, 0x6000
	v_lshlrev_b32_e32 v32, 16, v28
	s_waitcnt vmcnt(0)
	s_mov_b32 s98, 0
	s_and_b64 vcc, exec, s[14:15]
	s_cbranch_vccnz .Ln1_pfdone
	v_cmp_lt_i32_e32 vcc, -1, v85
	s_and_b32 s100, vcc_lo, 0xffff
	s_mov_b32 s101, 0
	s_cmp_eq_u64 s[100:101], 0
	s_cbranch_scc1 .Ln1_pfdone
	s_ff1_i32_b64 s11, s[100:101]
	s_add_u32 s16, s100, -1
	s_addc_u32 s17, s101, -1
	s_and_b64 s[100:101], s[16:17], s[100:101]
	s_cmp_eq_u64 s[100:101], 0
	s_cselect_b64 s[16:17], -1, 0
	s_ff1_i32_b64 s22, s[100:101]
	s_and_b64 vcc, s[16:17], exec
	s_cselect_b32 s22, s11, s22
	v_or_b32_e32 v218, s11, v86
	v_or_b32_e32 v219, s22, v86
	v_lshlrev_b32_e32 v218, 2, v218
	v_lshlrev_b32_e32 v219, 2, v219
	ds_bpermute_b32 v220, v218, v85
	ds_bpermute_b32 v221, v219, v85
	ds_bpermute_b32 v216, v218, v95
	ds_bpermute_b32 v217, v219, v95
	s_mulk_i32 s11, 0x600
	s_mulk_i32 s22, 0x600
	s_add_u32 s16, s100, -1
	s_addc_u32 s17, s101, -1
	s_and_b64 s[100:101], s[16:17], s[100:101]
	s_waitcnt lgkmcnt(0)
	v_add_u32_e32 v220, s11, v220
	v_add_u32_e32 v222, s22, v221
	v_ashrrev_i32_e32 v221, 31, v220
	v_ashrrev_i32_e32 v223, 31, v222
	v_lshlrev_b64 v[220:221], 11, v[220:221]
	v_lshlrev_b64 v[222:223], 11, v[222:223]
	v_lshl_add_u64 v[220:221], v[36:37], 0, v[220:221]
	v_lshl_add_u64 v[222:223], v[36:37], 0, v[222:223]
	global_load_dwordx2 v[200:201], v[220:221], off
	global_load_dwordx2 v[202:203], v[222:223], off
	global_load_dwordx2 v[204:205], v[220:221], off offset:512
	global_load_dwordx2 v[206:207], v[222:223], off offset:512
	global_load_dwordx2 v[208:209], v[220:221], off offset:1024
	global_load_dwordx2 v[210:211], v[222:223], off offset:1024
	global_load_dwordx2 v[212:213], v[220:221], off offset:1536
	global_load_dwordx2 v[214:215], v[222:223], off offset:1536
	v_mul_f32_e32 v216, 0x3e000000, v216
	v_mul_f32_e32 v217, 0x3e000000, v217
	s_cmp_eq_u32 s22, s11
	s_cbranch_scc0 .Ln1_two
	v_mov_b32_e32 v217, 0

.Ln1_pfdone:
	v_sub_f32_e32 v105, v96, v50
	ds_read_b128 v[96:99], v93
	ds_read_b128 v[100:103], v93 offset:8192
	v_sub_f32_e32 v104, v32, v50
	v_add_u32_e32 v32, s6, v93
	v_lshlrev_b32_e32 v28, 16, v29
	v_and_b32_e32 v29, 0xffff0000, v29
	v_pk_mul_f32 v[116:117], v[50:51], v[104:105] op_sel:[1,0]
	ds_read_b128 v[104:107], v93 offset:16
	ds_read_b128 v[108:111], v93 offset:8208
	ds_read_b128 v[112:115], v32 offset:32768
	v_sub_f32_e32 v29, v29, v50
	v_sub_f32_e32 v28, v28, v50
	v_pk_mul_f32 v[28:29], v[50:51], v[28:29] op_sel:[1,0]
	s_waitcnt lgkmcnt(3)
	v_pk_fma_f32 v[96:97], v[116:117], v[96:97], v[100:101]
	v_pk_fma_f32 v[28:29], v[28:29], v[98:99], v[102:103]
	v_pk_mul_f32 v[100:101], v[96:97], s[4:5] op_sel_hi:[1,0]
	v_pk_mul_f32 v[28:29], v[28:29], s[4:5] op_sel_hi:[1,0]
	ds_read_b128 v[96:99], v32 offset:32784
	s_waitcnt lgkmcnt(1)
	v_pk_fma_f32 v[28:29], v[82:83], v[114:115], v[28:29]
	v_lshlrev_b32_e32 v82, 16, v30
	v_and_b32_e32 v83, 0xffff0000, v30
	v_lshlrev_b32_e32 v30, 16, v31
	v_and_b32_e32 v31, 0xffff0000, v31
	v_sub_f32_e32 v83, v83, v50
	v_sub_f32_e32 v82, v82, v50
	v_sub_f32_e32 v31, v31, v50
	v_sub_f32_e32 v30, v30, v50
	v_pk_mul_f32 v[82:83], v[50:51], v[82:83] op_sel:[1,0]
	v_pk_mul_f32 v[30:31], v[50:51], v[30:31] op_sel:[1,0]
	v_pk_fma_f32 v[82:83], v[82:83], v[104:105], v[108:109]
	v_pk_fma_f32 v[30:31], v[30:31], v[106:107], v[110:111]
	v_pk_mul_f32 v[82:83], v[82:83], s[4:5] op_sel_hi:[1,0]
	v_pk_fma_f32 v[80:81], v[80:81], v[112:113], v[100:101]
	v_pk_mul_f32 v[30:31], v[30:31], s[4:5] op_sel_hi:[1,0]
	s_waitcnt lgkmcnt(0)
	v_pk_fma_f32 v[76:77], v[76:77], v[96:97], v[82:83]
	v_pk_fma_f32 v[30:31], v[78:79], v[98:99], v[30:31]
	v_mov_b32_e32 v78, v80
	v_mov_b32_e32 v79, v76
	v_mov_b32_e32 v82, v81
	v_mov_b32_e32 v83, v77
	v_pk_add_f32 v[78:79], v[78:79], v[82:83]
	v_mov_b32_e32 v82, v28
	v_mov_b32_e32 v83, v30
	v_mov_b32_e32 v96, v29
	v_mov_b32_e32 v97, v31
	v_pk_add_f32 v[82:83], v[82:83], v[96:97]
	ds_read_b128 v[96:99], v93 offset:2048
	ds_read_b128 v[100:103], v93 offset:10240
	v_pk_add_f32 v[78:79], v[78:79], v[82:83]
	v_lshlrev_b32_e32 v82, 16, v25
	v_add_f32_e32 v78, 0, v78
	v_add_f32_e32 v78, v78, v79
	v_lshlrev_b32_e32 v79, 16, v24
	v_and_b32_e32 v24, 0xffff0000, v24
	v_and_b32_e32 v83, 0xffff0000, v25
	ds_read_b128 v[104:107], v93 offset:2064
	ds_read_b128 v[108:111], v93 offset:10256
	ds_read_b128 v[112:115], v32 offset:34816
	v_sub_f32_e32 v25, v24, v50
	v_sub_f32_e32 v24, v79, v50
	v_sub_f32_e32 v83, v83, v50
	v_sub_f32_e32 v82, v82, v50
	v_pk_mul_f32 v[82:83], v[50:51], v[82:83] op_sel:[1,0]
	v_pk_mul_f32 v[24:25], v[50:51], v[24:25] op_sel:[1,0]
	s_waitcnt lgkmcnt(3)
	v_pk_fma_f32 v[82:83], v[82:83], v[98:99], v[102:103]
	v_pk_fma_f32 v[24:25], v[24:25], v[96:97], v[100:101]
	v_pk_mul_f32 v[82:83], v[82:83], s[4:5] op_sel_hi:[1,0]
	v_pk_mul_f32 v[24:25], v[24:25], s[4:5] op_sel_hi:[1,0]
	ds_read_b128 v[96:99], v32 offset:34832
	s_waitcnt lgkmcnt(1)
	v_pk_fma_f32 v[24:25], v[74:75], v[112:113], v[24:25]
	v_pk_fma_f32 v[72:73], v[72:73], v[114:115], v[82:83]
	v_mov_b32_e32 v82, v24
	v_pk_mov_b32 v[74:75], v[24:25], v[72:73] op_sel:[1,0]
	v_mov_b32_e32 v83, v73
	v_pk_add_f32 v[74:75], v[74:75], v[82:83]
	v_and_b32_e32 v79, 0xffff0000, v26
	v_pk_add_f32 v[74:75], v[74:75], v[74:75] op_sel:[0,1] op_sel_hi:[1,0]
	v_sub_f32_e32 v83, v79, v50
	v_lshlrev_b32_e32 v75, 16, v26
	v_lshlrev_b32_e32 v26, 16, v27
	v_and_b32_e32 v27, 0xffff0000, v27
	v_sub_f32_e32 v27, v27, v50
	v_sub_f32_e32 v26, v26, v50
	v_sub_f32_e32 v82, v75, v50
	v_pk_mul_f32 v[82:83], v[50:51], v[82:83] op_sel:[1,0]
	v_pk_mul_f32 v[26:27], v[50:51], v[26:27] op_sel:[1,0]
	v_pk_fma_f32 v[82:83], v[82:83], v[104:105], v[108:109]
	v_pk_fma_f32 v[26:27], v[26:27], v[106:107], v[110:111]
	v_pk_mul_f32 v[82:83], v[82:83], s[4:5] op_sel_hi:[1,0]
	v_pk_mul_f32 v[26:27], v[26:27], s[4:5] op_sel_hi:[1,0]
	s_waitcnt lgkmcnt(0)
	v_pk_fma_f32 v[68:69], v[68:69], v[96:97], v[82:83]
	v_pk_fma_f32 v[26:27], v[70:71], v[98:99], v[26:27]
	v_lshlrev_b32_e32 v71, 16, v20
	v_and_b32_e32 v75, 0xffff0000, v20
	ds_read_b128 v[96:99], v93 offset:4096
	ds_read_b128 v[100:103], v93 offset:12288
	v_sub_f32_e32 v105, v75, v50
	v_sub_f32_e32 v104, v71, v50
	v_lshlrev_b32_e32 v20, 16, v21
	v_and_b32_e32 v21, 0xffff0000, v21
	v_pk_mul_f32 v[116:117], v[50:51], v[104:105] op_sel:[1,0]
	ds_read_b128 v[104:107], v93 offset:4112
	ds_read_b128 v[108:111], v93 offset:12304
	ds_read_b128 v[112:115], v32 offset:36864
	v_sub_f32_e32 v21, v21, v50
	v_sub_f32_e32 v20, v20, v50
	v_pk_mul_f32 v[20:21], v[50:51], v[20:21] op_sel:[1,0]
	s_waitcnt lgkmcnt(3)
	v_pk_fma_f32 v[96:97], v[116:117], v[96:97], v[100:101]
	v_pk_fma_f32 v[20:21], v[20:21], v[98:99], v[102:103]
	v_pk_mul_f32 v[100:101], v[96:97], s[4:5] op_sel_hi:[1,0]
	v_pk_mul_f32 v[20:21], v[20:21], s[4:5] op_sel_hi:[1,0]
	ds_read_b128 v[96:99], v32 offset:36880
	s_waitcnt lgkmcnt(1)
	v_pk_fma_f32 v[20:21], v[66:67], v[114:115], v[20:21]
	v_pk_fma_f32 v[64:65], v[64:65], v[112:113], v[100:101]
	v_add_f32_e32 v70, v68, v69
	v_add_f32_e32 v82, v26, v27
	v_mov_b32_e32 v79, v64
	v_mov_b32_e32 v75, v65
	v_mov_b32_e32 v71, v20
	v_mov_b32_e32 v83, v21
	v_pk_add_f32 v[66:67], v[78:79], v[74:75]
	v_pk_add_f32 v[70:71], v[70:71], v[82:83]
	s_ashr_i32 s11, s10, 31
	v_pk_add_f32 v[66:67], v[66:67], v[70:71]
	v_lshlrev_b32_e32 v70, 16, v23
	v_pk_add_f32 v[66:67], v[66:67], v[66:67] op_sel:[0,1] op_sel_hi:[1,0]
	v_and_b32_e32 v71, 0xffff0000, v23
	v_lshlrev_b32_e32 v67, 16, v22
	v_and_b32_e32 v22, 0xffff0000, v22
	v_sub_f32_e32 v23, v22, v50
	v_sub_f32_e32 v22, v67, v50
	v_sub_f32_e32 v71, v71, v50
	v_sub_f32_e32 v70, v70, v50
	v_pk_mul_f32 v[70:71], v[50:51], v[70:71] op_sel:[1,0]
	v_pk_mul_f32 v[22:23], v[50:51], v[22:23] op_sel:[1,0]
	v_pk_fma_f32 v[70:71], v[70:71], v[106:107], v[110:111]
	v_pk_fma_f32 v[22:23], v[22:23], v[104:105], v[108:109]
	v_pk_mul_f32 v[70:71], v[70:71], s[4:5] op_sel_hi:[1,0]
	v_pk_mul_f32 v[22:23], v[22:23], s[4:5] op_sel_hi:[1,0]
	s_waitcnt lgkmcnt(0)
	v_pk_fma_f32 v[60:61], v[60:61], v[98:99], v[70:71]
	v_pk_fma_f32 v[22:23], v[62:63], v[96:97], v[22:23]
	v_mov_b32_e32 v71, v61
	v_pk_mov_b32 v[62:63], v[22:23], v[60:61] op_sel:[1,0]
	v_mov_b32_e32 v70, v22
	v_pk_add_f32 v[62:63], v[62:63], v[70:71]
	ds_read_b128 v[96:99], v93 offset:6144
	ds_read_b128 v[100:103], v93 offset:14336
	v_pk_add_f32 v[62:63], v[62:63], v[62:63] op_sel:[0,1] op_sel_hi:[1,0]
	v_and_b32_e32 v67, 0xffff0000, v16
	v_lshlrev_b32_e32 v63, 16, v16
	v_lshlrev_b32_e32 v16, 16, v17
	v_and_b32_e32 v17, 0xffff0000, v17
	ds_read_b128 v[104:107], v93 offset:6160
	ds_read_b128 v[108:111], v93 offset:14352
	ds_read_b128 v[112:115], v32 offset:38912
	v_sub_f32_e32 v17, v17, v50
	v_sub_f32_e32 v16, v16, v50
	v_pk_mul_f32 v[16:17], v[50:51], v[16:17] op_sel:[1,0]
	v_sub_f32_e32 v71, v67, v50
	v_sub_f32_e32 v70, v63, v50
	s_waitcnt lgkmcnt(3)
	v_pk_fma_f32 v[16:17], v[16:17], v[98:99], v[102:103]
	v_pk_mul_f32 v[70:71], v[50:51], v[70:71] op_sel:[1,0]
	v_pk_mul_f32 v[16:17], v[16:17], s[4:5] op_sel_hi:[1,0]
	v_pk_fma_f32 v[70:71], v[70:71], v[96:97], v[100:101]
	ds_read_b128 v[96:99], v32 offset:38928
	s_waitcnt lgkmcnt(1)
	v_pk_fma_f32 v[58:59], v[58:59], v[114:115], v[16:17]
	v_lshlrev_b32_e32 v32, 16, v18
	v_and_b32_e32 v18, 0xffff0000, v18
	v_lshlrev_b32_e32 v16, 16, v19
	v_and_b32_e32 v17, 0xffff0000, v19
	v_sub_f32_e32 v17, v17, v50
	v_sub_f32_e32 v16, v16, v50
	v_sub_f32_e32 v19, v18, v50
	v_sub_f32_e32 v18, v32, v50
	v_pk_mul_f32 v[18:19], v[50:51], v[18:19] op_sel:[1,0]
	v_pk_mul_f32 v[16:17], v[50:51], v[16:17] op_sel:[1,0]
	v_pk_fma_f32 v[18:19], v[18:19], v[104:105], v[108:109]
	v_pk_fma_f32 v[16:17], v[16:17], v[106:107], v[110:111]
	v_pk_mul_f32 v[70:71], v[70:71], s[4:5] op_sel_hi:[1,0]
	v_pk_mul_f32 v[18:19], v[18:19], s[4:5] op_sel_hi:[1,0]
	v_pk_mul_f32 v[16:17], v[16:17], s[4:5] op_sel_hi:[1,0]
	v_pk_fma_f32 v[56:57], v[56:57], v[112:113], v[70:71]
	s_waitcnt lgkmcnt(0)
	v_pk_fma_f32 v[16:17], v[54:55], v[98:99], v[16:17]
	v_pk_fma_f32 v[18:19], v[52:53], v[96:97], v[18:19]
	v_add_f32_e32 v70, v56, v57
	v_add_f32_e32 v74, v58, v59
	v_mov_b32_e32 v67, v18
	v_mov_b32_e32 v63, v19
	v_mov_b32_e32 v71, v16
	v_mov_b32_e32 v75, v17
	v_pk_add_f32 v[50:51], v[66:67], v[62:63]
	v_pk_add_f32 v[52:53], v[70:71], v[74:75]
	s_lshl_b64 s[10:11], s[10:11], 13
	v_pk_add_f32 v[50:51], v[50:51], v[52:53]
	s_nop 0
	v_add_f32_e32 v32, v50, v51
	ds_bpermute_b32 v50, v87, v32
	s_waitcnt lgkmcnt(0)
	v_add_f32_e32 v32, v32, v50
	ds_bpermute_b32 v50, v88, v32
	s_waitcnt lgkmcnt(0)
	v_add_f32_e32 v32, v32, v50
	ds_bpermute_b32 v50, v89, v32
	s_waitcnt lgkmcnt(0)
	v_add_f32_e32 v32, v32, v50
	ds_bpermute_b32 v50, v90, v32
	s_waitcnt lgkmcnt(0)
	v_add_f32_e32 v32, v32, v50
	ds_bpermute_b32 v50, v91, v32
	s_waitcnt lgkmcnt(0)
	v_add_f32_e32 v32, v32, v50
	ds_bpermute_b32 v50, v92, v32
	s_waitcnt lgkmcnt(0)
	v_add_f32_e32 v66, v32, v50
	v_fmamk_f32 v81, v66, 0xba000000, v81
	v_fmamk_f32 v77, v66, 0xba000000, v77
	v_fmamk_f32 v29, v66, 0xba000000, v29
	v_fmac_f32_e32 v80, 0xba000000, v66
	v_fmamk_f32 v31, v66, 0xba000000, v31
	v_fmac_f32_e32 v76, 0xba000000, v66
	v_mov_b32_e32 v52, v81
	v_mov_b32_e32 v53, v77
	v_fmac_f32_e32 v28, 0xba000000, v66
	v_fmac_f32_e32 v30, 0xba000000, v66
	v_mov_b32_e32 v50, v80
	v_mov_b32_e32 v51, v76
	v_pk_mul_f32 v[52:53], v[52:53], v[52:53]
	v_mov_b32_e32 v54, v29
	v_mov_b32_e32 v55, v31
	v_pk_fma_f32 v[50:51], v[50:51], v[50:51], v[52:53]
	v_mov_b32_e32 v52, v28
	v_mov_b32_e32 v53, v30
	v_pk_mul_f32 v[54:55], v[54:55], v[54:55]
	v_fmamk_f32 v25, v66, 0xba000000, v25
	v_pk_fma_f32 v[52:53], v[52:53], v[52:53], v[54:55]
	v_fmac_f32_e32 v24, 0xba000000, v66
	v_fmamk_f32 v73, v66, 0xba000000, v73
	v_fmac_f32_e32 v72, 0xba000000, v66
	v_pk_add_f32 v[50:51], v[50:51], v[52:53]
	v_pk_mul_f32 v[52:53], v[72:73], v[72:73]
	v_pk_mul_f32 v[54:55], v[24:25], v[24:25]
	v_fmac_f32_e32 v68, 0xba000000, v66
	v_pk_mov_b32 v[62:63], v[54:55], v[52:53] op_sel:[1,0]
	v_mov_b32_e32 v55, v53
	v_fmamk_f32 v69, v66, 0xba000000, v69
	v_fmac_f32_e32 v26, 0xba000000, v66
	v_mul_f32_e32 v32, v68, v68
	v_pk_add_f32 v[52:53], v[62:63], v[54:55]
	v_fmamk_f32 v27, v66, 0xba000000, v27
	v_pk_fma_f32 v[54:55], v[68:69], v[68:69], v[32:33] op_sel_hi:[1,1,0]
	v_mul_f32_e32 v32, v26, v26
	v_pk_add_f32 v[50:51], v[50:51], v[50:51] op_sel_hi:[0,1]
	v_pk_add_f32 v[52:53], v[52:53], v[52:53] op_sel_hi:[0,1]
	v_pk_fma_f32 v[62:63], v[26:27], v[26:27], v[32:33] op_sel_hi:[1,1,0]
	v_fmamk_f32 v21, v66, 0xba000000, v21
	v_fmac_f32_e32 v20, 0xba000000, v66
	v_fmamk_f32 v65, v66, 0xba000000, v65
	v_fmac_f32_e32 v64, 0xba000000, v66
	v_mul_f32_e32 v54, v64, v64
	v_mul_f32_e32 v62, v65, v65
	v_mul_f32_e32 v52, v20, v20
	v_mul_f32_e32 v50, v21, v21
	v_pk_add_f32 v[54:55], v[54:55], v[62:63]
	v_pk_add_f32 v[50:51], v[52:53], v[50:51]
	v_fmamk_f32 v23, v66, 0xba000000, v23
	v_fmac_f32_e32 v22, 0xba000000, v66
	v_fmamk_f32 v61, v66, 0xba000000, v61
	v_fmac_f32_e32 v60, 0xba000000, v66
	v_pk_add_f32 v[50:51], v[54:55], v[50:51]
	v_pk_mul_f32 v[52:53], v[60:61], v[60:61]
	v_pk_mul_f32 v[54:55], v[22:23], v[22:23]
	v_fmac_f32_e32 v56, 0xba000000, v66
	v_pk_mov_b32 v[62:63], v[54:55], v[52:53] op_sel:[1,0]
	v_mov_b32_e32 v55, v53
	v_fmamk_f32 v57, v66, 0xba000000, v57
	v_fmac_f32_e32 v58, 0xba000000, v66
	v_mul_f32_e32 v32, v56, v56
	v_pk_add_f32 v[52:53], v[62:63], v[54:55]
	v_fmamk_f32 v59, v66, 0xba000000, v59
	v_pk_fma_f32 v[54:55], v[56:57], v[56:57], v[32:33] op_sel_hi:[1,1,0]
	v_mul_f32_e32 v32, v58, v58
	v_pk_add_f32 v[50:51], v[50:51], v[50:51] op_sel_hi:[0,1]
	v_pk_add_f32 v[52:53], v[52:53], v[52:53] op_sel_hi:[0,1]
	v_pk_fma_f32 v[62:63], v[58:59], v[58:59], v[32:33] op_sel_hi:[1,1,0]
	v_fmamk_f32 v17, v66, 0xba000000, v17
	v_fmac_f32_e32 v16, 0xba000000, v66
	v_fmamk_f32 v19, v66, 0xba000000, v19
	v_fmac_f32_e32 v18, 0xba000000, v66
	v_mul_f32_e32 v54, v18, v18
	v_mul_f32_e32 v62, v19, v19
	v_mul_f32_e32 v52, v16, v16
	v_mul_f32_e32 v50, v17, v17
	v_pk_add_f32 v[54:55], v[54:55], v[62:63]
	v_pk_add_f32 v[50:51], v[52:53], v[50:51]
	s_nop 0
	v_pk_add_f32 v[50:51], v[54:55], v[50:51]
	s_nop 0
	v_add_f32_e32 v32, v50, v51
	ds_bpermute_b32 v50, v87, v32
	s_waitcnt lgkmcnt(0)
	v_add_f32_e32 v32, v32, v50
	ds_bpermute_b32 v50, v88, v32
	s_waitcnt lgkmcnt(0)
	v_add_f32_e32 v32, v32, v50
	ds_bpermute_b32 v50, v89, v32
	s_waitcnt lgkmcnt(0)
	v_add_f32_e32 v32, v32, v50
	ds_bpermute_b32 v50, v90, v32
	s_waitcnt lgkmcnt(0)
	v_add_f32_e32 v32, v32, v50
	ds_bpermute_b32 v50, v91, v32
	s_waitcnt lgkmcnt(0)
	v_add_f32_e32 v32, v32, v50
	ds_bpermute_b32 v50, v92, v32
	s_waitcnt lgkmcnt(0)
	v_add_f32_e32 v32, v32, v50
	v_fmamk_f32 v32, v32, 0x3a000000, v94
	v_mul_f32_e32 v50, 0x4b800000, v32
	v_cmp_gt_f32_e32 vcc, s5, v32
	s_nop 1
	v_cndmask_b32_e32 v32, v32, v50, vcc
	v_rsq_f32_e32 v32, v32
	s_nop 0
	v_mul_f32_e32 v50, 0x45800000, v32
	v_cndmask_b32_e32 v32, v32, v50, vcc
	ds_read_b128 v[50:53], v93 offset:16384
	ds_read_b128 v[96:99], v93 offset:24576
	v_pk_mul_f32 v[54:55], v[80:81], v[32:33] op_sel_hi:[1,0]
	ds_read_b128 v[78:81], v93 offset:16400
	ds_read_b128 v[100:103], v93 offset:24592
	v_pk_mul_f32 v[28:29], v[28:29], v[32:33] op_sel_hi:[1,0]
	v_pk_mul_f32 v[30:31], v[30:31], v[32:33] op_sel_hi:[1,0]
	s_waitcnt lgkmcnt(2)
	v_pk_fma_f32 v[52:53], v[52:53], v[28:29], v[98:99]
	v_pk_mul_f32 v[28:29], v[76:77], v[32:33] op_sel_hi:[1,0]
	v_pk_fma_f32 v[50:51], v[50:51], v[54:55], v[96:97]
	v_lshl_add_u64 v[54:55], v[38:39], 0, s[10:11]
	s_waitcnt lgkmcnt(0)
	v_pk_fma_f32 v[30:31], v[80:81], v[30:31], v[102:103]
	v_pk_fma_f32 v[28:29], v[78:79], v[28:29], v[100:101]
	global_store_dwordx4 v[54:55], v[50:53], off
	global_store_dwordx4 v[54:55], v[28:31], off offset:16
	ds_read_b128 v[28:31], v93 offset:18432
	ds_read_b128 v[50:53], v93 offset:26624
	v_pk_mul_f32 v[62:63], v[72:73], v[32:33] op_sel_hi:[1,0]
	ds_read_b128 v[70:73], v93 offset:18448
	ds_read_b128 v[74:77], v93 offset:26640
	v_pk_mul_f32 v[24:25], v[24:25], v[32:33] op_sel_hi:[1,0]
	v_pk_mul_f32 v[26:27], v[26:27], v[32:33] op_sel_hi:[1,0]
	s_waitcnt lgkmcnt(2)
	v_pk_fma_f32 v[28:29], v[28:29], v[24:25], v[50:51]
	v_pk_mul_f32 v[24:25], v[68:69], v[32:33] op_sel_hi:[1,0]
	v_pk_fma_f32 v[30:31], v[30:31], v[62:63], v[52:53]
	s_waitcnt lgkmcnt(0)
	v_pk_fma_f32 v[26:27], v[72:73], v[26:27], v[76:77]
	v_pk_fma_f32 v[24:25], v[70:71], v[24:25], v[74:75]
	global_store_dwordx4 v[54:55], v[28:31], off offset:2048
	global_store_dwordx4 v[54:55], v[24:27], off offset:2064
	ds_read_b128 v[24:27], v93 offset:20480
	ds_read_b128 v[28:31], v93 offset:28672
	v_pk_mul_f32 v[54:55], v[64:65], v[32:33] op_sel_hi:[1,0]
	ds_read_b128 v[50:53], v93 offset:20496
	ds_read_b128 v[62:65], v93 offset:28688
	v_pk_mul_f32 v[20:21], v[20:21], v[32:33] op_sel_hi:[1,0]
	s_and_b64 vcc, exec, s[14:15]
	s_waitcnt lgkmcnt(2)
	v_pk_fma_f32 v[26:27], v[26:27], v[20:21], v[30:31]
	v_pk_fma_f32 v[24:25], v[24:25], v[54:55], v[28:29]
	v_lshl_add_u64 v[20:21], v[40:41], 0, s[10:11]
	global_store_dwordx4 v[20:21], v[24:27], off
	v_pk_mul_f32 v[20:21], v[22:23], v[32:33] op_sel_hi:[1,0]
	v_pk_mul_f32 v[22:23], v[60:61], v[32:33] op_sel_hi:[1,0]
	s_waitcnt lgkmcnt(0)
	v_pk_fma_f32 v[20:21], v[50:51], v[20:21], v[62:63]
	v_pk_fma_f32 v[22:23], v[52:53], v[22:23], v[64:65]
	v_lshl_add_u64 v[24:25], v[42:43], 0, s[10:11]
	global_store_dwordx4 v[24:25], v[20:23], off
	ds_read_b128 v[20:23], v93 offset:22528
	ds_read_b128 v[24:27], v93 offset:30720
	ds_read_b128 v[28:31], v93 offset:22544
	ds_read_b128 v[50:53], v93 offset:30736
	v_pk_mul_f32 v[54:55], v[56:57], v[32:33] op_sel_hi:[1,0]
	v_pk_mul_f32 v[56:57], v[58:59], v[32:33] op_sel_hi:[1,0]
	v_mov_b32_e32 v96, v85
	s_waitcnt lgkmcnt(2)
	v_pk_fma_f32 v[22:23], v[22:23], v[56:57], v[26:27]
	v_pk_fma_f32 v[20:21], v[20:21], v[54:55], v[24:25]
	v_lshl_add_u64 v[24:25], v[44:45], 0, s[10:11]
	global_store_dwordx4 v[24:25], v[20:23], off
	v_mov_b64_e32 v[26:27], v[6:7]
	v_mov_b64_e32 v[24:25], v[4:5]
	v_pk_mul_f32 v[20:21], v[16:17], v[32:33] op_sel_hi:[1,0]
	v_pk_mul_f32 v[16:17], v[18:19], v[32:33] op_sel_hi:[1,0]
	s_waitcnt lgkmcnt(0)
	v_pk_fma_f32 v[18:19], v[30:31], v[20:21], v[52:53]
	v_pk_fma_f32 v[16:17], v[28:29], v[16:17], v[50:51]
	v_lshl_add_u64 v[20:21], v[46:47], 0, s[10:11]
	global_store_dwordx4 v[20:21], v[16:19], off
	v_mov_b64_e32 v[30:31], v[2:3]
	v_mov_b64_e32 v[22:23], v[10:11]
	v_mov_b64_e32 v[18:19], v[14:15]
	v_mov_b64_e32 v[28:29], v[0:1]
	v_mov_b64_e32 v[20:21], v[8:9]
	v_mov_b64_e32 v[16:17], v[12:13]
	v_mov_b32_e32 v97, v95
	v_mov_b64_e32 v[50:51], v[48:49]
	s_mov_b32 s10, s12
	s_cbranch_vccnz .LBB0_3062

.LBB0_3057:
	s_waitcnt vmcnt(2)
	v_cmp_lt_i32_e32 vcc, -1, v96
	s_and_b32 s6, vcc_lo, 0xffff
	s_cmp_eq_u64 s[6:7], 0
	s_cbranch_scc1 .LBB0_3051
	v_mov_b32_e32 v80, 0
	s_mov_b64 s[16:17], s[6:7]
	v_mov_b32_e32 v81, v80
	v_mov_b32_e32 v82, v80
	v_mov_b32_e32 v83, v80
	v_mov_b32_e32 v76, v80
	v_mov_b32_e32 v77, v80
	v_mov_b32_e32 v78, v80
	v_mov_b32_e32 v79, v80
	v_mov_b32_e32 v74, v80
	v_mov_b32_e32 v75, v80
	v_mov_b32_e32 v72, v80
	v_mov_b32_e32 v73, v80
	v_mov_b32_e32 v68, v80
	v_mov_b32_e32 v69, v80
	v_mov_b32_e32 v70, v80
	v_mov_b32_e32 v71, v80
	v_mov_b32_e32 v64, v80
	v_mov_b32_e32 v65, v80
	v_mov_b32_e32 v66, v80
	v_mov_b32_e32 v67, v80
	v_mov_b32_e32 v62, v80
	v_mov_b32_e32 v63, v80
	v_mov_b32_e32 v60, v80
	v_mov_b32_e32 v61, v80
	v_mov_b32_e32 v56, v80
	v_mov_b32_e32 v57, v80
	v_mov_b32_e32 v58, v80
	v_mov_b32_e32 v59, v80
	v_mov_b32_e32 v52, v80
	v_mov_b32_e32 v53, v80
	v_mov_b32_e32 v54, v80
	v_mov_b32_e32 v55, v80
	s_cmp_eq_u32 s98, 0
	s_cbranch_scc1 .LBB0_3060
	v_mov_b32_e32 v98, v216
	v_mov_b32_e32 v32, v217
	v_mov_b32_e32 v99, v217
	v_cvt_pk_f32_fp8_e32 v[122:123], v202
	v_cvt_pk_f32_fp8_sdwa v[124:125], v202 src0_sel:WORD_1
	v_cvt_pk_f32_fp8_e32 v[126:127], v203
	v_cvt_pk_f32_fp8_sdwa v[202:203], v203 src0_sel:WORD_1
	v_cvt_pk_f32_fp8_e32 v[134:135], v206
	v_cvt_pk_f32_fp8_e32 v[152:153], v212
	v_cvt_pk_f32_fp8_sdwa v[154:155], v212 src0_sel:WORD_1
	v_cvt_pk_f32_fp8_e32 v[156:157], v213
	v_cvt_pk_f32_fp8_sdwa v[212:213], v213 src0_sel:WORD_1
	v_cvt_pk_f32_fp8_e32 v[158:159], v214
	v_cvt_pk_f32_fp8_sdwa v[160:161], v214 src0_sel:WORD_1
	v_cvt_pk_f32_fp8_e32 v[162:163], v215
	v_cvt_pk_f32_fp8_sdwa v[214:215], v215 src0_sel:WORD_1
	v_cvt_pk_f32_fp8_sdwa v[136:137], v206 src0_sel:WORD_1
	v_cvt_pk_f32_fp8_e32 v[138:139], v207
	v_cvt_pk_f32_fp8_sdwa v[206:207], v207 src0_sel:WORD_1
	v_cvt_pk_f32_fp8_e32 v[146:147], v210
	v_cvt_pk_f32_fp8_sdwa v[148:149], v210 src0_sel:WORD_1
	v_cvt_pk_f32_fp8_e32 v[150:151], v211
	v_cvt_pk_f32_fp8_sdwa v[210:211], v211 src0_sel:WORD_1
	v_cvt_pk_f32_fp8_e32 v[100:101], v200
	v_cvt_pk_f32_fp8_sdwa v[102:103], v200 src0_sel:WORD_1
	v_cvt_pk_f32_fp8_e32 v[120:121], v201
	v_cvt_pk_f32_fp8_sdwa v[200:201], v201 src0_sel:WORD_1
	v_cvt_pk_f32_fp8_e32 v[128:129], v204
	v_cvt_pk_f32_fp8_sdwa v[130:131], v204 src0_sel:WORD_1
	v_cvt_pk_f32_fp8_e32 v[132:133], v205
	v_cvt_pk_f32_fp8_sdwa v[204:205], v205 src0_sel:WORD_1
	v_cvt_pk_f32_fp8_e32 v[140:141], v208
	v_cvt_pk_f32_fp8_sdwa v[142:143], v208 src0_sel:WORD_1
	v_cvt_pk_f32_fp8_e32 v[144:145], v209
	v_cvt_pk_f32_fp8_sdwa v[208:209], v209 src0_sel:WORD_1
	v_mul_f32_e32 v164, v32, v214
	v_mov_b32_e32 v214, v213
	v_pk_mul_f32 v[122:123], v[32:33], v[122:123] op_sel_hi:[0,1]
	v_pk_mul_f32 v[124:125], v[32:33], v[124:125] op_sel_hi:[0,1]
	v_pk_mul_f32 v[126:127], v[32:33], v[126:127] op_sel_hi:[0,1]
	v_pk_mul_f32 v[202:203], v[32:33], v[202:203] op_sel_hi:[0,1]
	v_pk_mul_f32 v[134:135], v[32:33], v[134:135] op_sel_hi:[0,1]
	v_pk_mul_f32 v[136:137], v[32:33], v[136:137] op_sel_hi:[0,1]
	v_pk_mul_f32 v[138:139], v[32:33], v[138:139] op_sel_hi:[0,1]
	v_pk_mul_f32 v[206:207], v[32:33], v[206:207] op_sel_hi:[0,1]
	v_pk_mul_f32 v[146:147], v[32:33], v[146:147] op_sel_hi:[0,1]
	v_pk_mul_f32 v[148:149], v[32:33], v[148:149] op_sel_hi:[0,1]
	v_pk_mul_f32 v[150:151], v[32:33], v[150:151] op_sel_hi:[0,1]
	v_pk_mul_f32 v[210:211], v[32:33], v[210:211] op_sel_hi:[0,1]
	v_pk_mul_f32 v[158:159], v[32:33], v[158:159] op_sel_hi:[0,1]
	v_pk_mul_f32 v[160:161], v[32:33], v[160:161] op_sel_hi:[0,1]
	v_pk_mul_f32 v[162:163], v[32:33], v[162:163] op_sel_hi:[0,1]
	v_pk_mul_f32 v[214:215], v[98:99], v[214:215]
	v_mul_f32_e32 v212, v98, v212
	v_pk_fma_f32 v[100:101], v[98:99], v[100:101], v[122:123] op_sel_hi:[0,1,1]
	v_pk_fma_f32 v[102:103], v[98:99], v[102:103], v[124:125] op_sel_hi:[0,1,1]
	v_pk_fma_f32 v[120:121], v[98:99], v[120:121], v[126:127] op_sel_hi:[0,1,1]
	v_pk_fma_f32 v[200:201], v[98:99], v[200:201], v[202:203] op_sel_hi:[0,1,1]
	v_pk_fma_f32 v[202:203], v[98:99], v[128:129], v[134:135] op_sel_hi:[0,1,1]
	v_pk_fma_f32 v[122:123], v[98:99], v[130:131], v[136:137] op_sel_hi:[0,1,1]
	v_pk_fma_f32 v[124:125], v[98:99], v[132:133], v[138:139] op_sel_hi:[0,1,1]
	v_pk_fma_f32 v[204:205], v[98:99], v[204:205], v[206:207] op_sel_hi:[0,1,1]
	v_pk_fma_f32 v[206:207], v[98:99], v[140:141], v[146:147] op_sel_hi:[0,1,1]
	v_pk_fma_f32 v[126:127], v[98:99], v[142:143], v[148:149] op_sel_hi:[0,1,1]
	v_pk_fma_f32 v[128:129], v[98:99], v[144:145], v[150:151] op_sel_hi:[0,1,1]
	v_pk_fma_f32 v[208:209], v[98:99], v[208:209], v[210:211] op_sel_hi:[0,1,1]
	v_pk_fma_f32 v[210:211], v[98:99], v[152:153], v[158:159] op_sel_hi:[0,1,1]
	v_pk_fma_f32 v[130:131], v[98:99], v[154:155], v[160:161] op_sel_hi:[0,1,1]
	v_pk_fma_f32 v[98:99], v[98:99], v[156:157], v[162:163] op_sel_hi:[0,1,1]
	v_mov_b32_e32 v213, v214
	v_mov_b32_e32 v165, v215
	v_pk_add_f32 v[52:53], v[52:53], v[98:99]
	v_pk_add_f32 v[98:99], v[212:213], v[164:165]
	v_pk_add_f32 v[58:59], v[58:59], v[130:131]
	v_pk_add_f32 v[54:55], v[54:55], v[98:99]
	v_pk_add_f32 v[56:57], v[56:57], v[210:211]
	v_pk_add_f32 v[60:61], v[60:61], v[208:209]
	v_pk_add_f32 v[62:63], v[62:63], v[128:129]
	v_pk_add_f32 v[66:67], v[66:67], v[126:127]
	v_pk_add_f32 v[64:65], v[64:65], v[206:207]
	v_pk_add_f32 v[70:71], v[70:71], v[204:205]
	v_pk_add_f32 v[68:69], v[68:69], v[124:125]
	v_pk_add_f32 v[72:73], v[72:73], v[122:123]
	v_pk_add_f32 v[74:75], v[74:75], v[202:203]
	v_pk_add_f32 v[78:79], v[78:79], v[200:201]
	v_pk_add_f32 v[76:77], v[76:77], v[120:121]
	v_pk_add_f32 v[82:83], v[82:83], v[102:103]
	v_pk_add_f32 v[80:81], v[80:81], v[100:101]
	s_mov_b64 s[16:17], s[100:101]
	s_cmp_eq_u64 s[16:17], 0
	s_cbranch_scc1 .LBB0_3052
	s_branch .LBB0_3060
